# phase E K loop: next step's LDS read addresses computed before the end-of-step wait (same as phase A)
# baseline (speedup 1.0000x reference)
; #define MFMA16(a, b, c) __builtin_amdgcn_mfma_f32_16x16x32_bf16((a), (b), (c), 0, 0, 0)
; DI void gemm_tile(const bf16_t* __restrict__ A, int lda, const bf16_t* __restrict__ Bt, int ldb, int bvalid, int K, f32x4 (&acc)[4][4], char* lds, bool preloaded = false) {
;     ...
;   const bf16_t* ap = A + (size_t)lr * lda + ((lc ^ ((lr >> 1) & 7)) << 3);
;   const bf16_t* bp = Bt + ((lc ^ ((lr >> 1) & 7)) << 3);
;   typedef __attribute__((address_space(1))) const unsigned gptr_t;
;   typedef __attribute__((address_space(3))) unsigned lptr_t;
;   const unsigned lbase = (unsigned)(size_t)lds + (unsigned)tid * 16u;
;     ...
;   auto compute = [&](int st) {
;     const char* base = lds + st * 32768;
;     bf16x8 af[2][4], bfr[2][4];
; #pragma unroll
;     for (int s = 0; s < 2; ++s) {
;       const int ch = ((4 * s + fq) ^ fx) << 4;
; #pragma unroll
;       for (int mi = 0; mi < 4; ++mi) af[s][mi] = *(const bf16x8*)(base + (wm * 64 + mi * 16 + fr) * 128 + ch);
; #pragma unroll
;       for (int ni = 0; ni < 4; ++ni) bfr[s][ni] = *(const bf16x8*)(base + 16384 + (wn * 64 + ni * 16 + fr) * 128 + ch);
;     }
;     __builtin_amdgcn_s_setprio(1);
; #pragma unroll
;     for (int s = 0; s < 2; ++s)
; #pragma unroll
;       for (int mi = 0; mi < 4; ++mi)
; #pragma unroll
;         for (int ni = 0; ni < 4; ++ni) acc[mi][ni] = MFMA16(af[s][mi], bfr[s][ni], acc[mi][ni]);
;     __builtin_amdgcn_s_setprio(0);
;   };
;   const int nk = K >> 6;
;   if (!preloaded) { GLDS(0, 0) }
; DI void phaseE_tile(const P& p, int layer, int mt, int nt, char* lds) {
;     ...
;   const int col = col0 + wn * 64 + fr * 4;
;   f32x4 xr[16];
; #pragma unroll
;   for (int ps = 0; ps < 16; ++ps) {
;     const int row = row0 + ps * 8 + wm * 4 + fq;
;     const float* xin = (layer == 0) ? ((row < NTP) ? p.x_p + (size_t)row * DM : p.x_s + (size_t)(row - NTP) * DM) : XF + (size_t)row * DM;
;     xr[ps] = __builtin_nontemporal_load((const f32x4*)(xin + col));
;   }
.LBB0_169:
	s_mul_i32 s8, s10, 0x880
	s_mul_hi_i32 s9, s10, 0x880
	s_add_u32 s24, s58, s8
	s_addc_u32 s25, s59, s9
	s_add_u32 s40, s24, 0x80
	s_addc_u32 s41, s25, 0
	s_ashr_i32 s23, s22, 31
	s_add_u32 s26, s4, s22
	s_addc_u32 s23, s5, s23
	v_mov_b32_e32 v76, v158
	s_mulk_i32 s23, 0x880
	s_mul_hi_u32 s27, s26, 0x880
	s_add_i32 s27, s27, s23
	v_lshrrev_b32_e32 v78, 4, v76
	s_mulk_i32 s26, 0x880
	v_readlane_b32 s28, v240, 31
	v_xor_b32_e32 v0, v78, v76
	v_readlane_b32 s29, v240, 32
	s_add_u32 s26, s28, s26
	v_ashrrev_i32_e32 v77, 3, v76
	v_mov_b64_e32 v[66:67], s[24:25]
	s_movk_i32 s28, 0x880
	v_lshlrev_b32_e32 v0, 4, v0
	s_addc_u32 s27, s29, s27
	s_add_u32 s42, s26, 0x80
	s_addc_u32 s43, s27, 0
	v_mad_i64_i32 v[66:67], s[24:25], v77, s28, v[66:67]
	v_and_b32_e32 v0, 0x70, v0
	v_lshl_add_u64 v[66:67], v[66:67], 0, v[0:1]
	v_lshl_add_u64 v[68:69], s[26:27], 0, v[0:1]
	v_lshlrev_b32_e32 v145, 4, v76
	v_and_b32_e32 v0, 0x7f, v77
	v_add_u32_e32 v72, 0x4000, v145
	v_readfirstlane_b32 s24, v145
	v_mul_u32_u24_e32 v0, 0x440, v0
	s_mov_b32 m0, s24
	v_lshlrev_b32_e32 v0, 1, v0
	v_readfirstlane_b32 s24, v72
	global_load_lds_dwordx4 v[66:67], off
	v_lshl_add_u64 v[70:71], v[68:69], 0, v[0:1]
	s_mov_b32 m0, s24
	s_mov_b64 s[24:25], 0x11000
	v_add_u32_e32 v72, 0x1000, v145
	global_load_lds_dwordx4 v[70:71], off
	v_lshl_add_u64 v[70:71], v[66:67], 0, s[24:25]
	v_readfirstlane_b32 s24, v72
	s_mov_b32 m0, s24
	v_add_u32_e32 v74, 0x5000, v145
	global_load_lds_dwordx4 v[70:71], off
	v_add_u32_e32 v70, 32, v77
	v_and_b32_e32 v70, 0x7f, v70
	v_mul_u32_u24_e32 v70, 0x440, v70
	v_lshlrev_b32_e32 v70, 1, v70
	v_mov_b32_e32 v71, v1
	v_readfirstlane_b32 s24, v74
	v_lshl_add_u64 v[72:73], v[68:69], 0, v[70:71]
	s_mov_b32 m0, s24
	s_mov_b64 s[24:25], 0x22000
	v_add_u32_e32 v74, 0x2000, v145
	global_load_lds_dwordx4 v[72:73], off
	v_lshl_add_u64 v[72:73], v[66:67], 0, s[24:25]
	v_readfirstlane_b32 s24, v74
	s_mov_b32 m0, s24
	v_add_u32_e32 v82, 0x6000, v145
	global_load_lds_dwordx4 v[72:73], off
	v_bitop3_b32 v72, v77, 64, v166 bitop3:0x6c
	v_mul_u32_u24_e32 v72, 0x440, v72
	v_lshlrev_b32_e32 v72, 1, v72
	v_mov_b32_e32 v73, v1
	v_readfirstlane_b32 s24, v82
	v_lshl_add_u64 v[74:75], v[68:69], 0, v[72:73]
	s_mov_b32 m0, s24
	s_mov_b64 s[24:25], 0x33000
	global_load_lds_dwordx4 v[74:75], off
	v_add_u32_e32 v74, 0x3000, v145
	v_lshl_add_u64 v[66:67], v[66:67], 0, s[24:25]
	v_readfirstlane_b32 s24, v74
	s_mov_b32 m0, s24
	v_add_u32_e32 v74, 0x7000, v145
	global_load_lds_dwordx4 v[66:67], off
	v_add_u32_e32 v66, 0x60, v77
	v_and_b32_e32 v66, 0x7f, v66
	v_mul_u32_u24_e32 v66, 0x440, v66
	v_lshlrev_b32_e32 v66, 1, v66
	v_mov_b32_e32 v67, v1
	v_readfirstlane_b32 s24, v74
	v_lshl_add_u64 v[68:69], v[68:69], 0, v[66:67]
	s_mov_b32 m0, s24
	v_readfirstlane_b32 s23, v76
	global_load_lds_dwordx4 v[68:69], off
	global_load_dwordx4 v[2:5], v242, s[36:37] nt
	s_add_u32 s36, s36, 0x8000
	s_addc_u32 s37, s37, 0
	global_load_dwordx4 v[6:9], v242, s[36:37] nt
	s_add_u32 s36, s36, 0x8000
	s_addc_u32 s37, s37, 0
	global_load_dwordx4 v[10:13], v242, s[36:37] nt
	s_add_u32 s36, s36, 0x8000
	s_addc_u32 s37, s37, 0
	global_load_dwordx4 v[14:17], v242, s[36:37] nt
	s_add_u32 s36, s36, 0x8000
	s_addc_u32 s37, s37, 0
	global_load_dwordx4 v[18:21], v242, s[36:37] nt
	s_add_u32 s36, s36, 0x8000
	s_addc_u32 s37, s37, 0
	global_load_dwordx4 v[22:25], v242, s[36:37] nt
	s_add_u32 s36, s36, 0x8000
	s_addc_u32 s37, s37, 0
	global_load_dwordx4 v[26:29], v242, s[36:37] nt
	s_add_u32 s36, s36, 0x8000
	s_addc_u32 s37, s37, 0
	global_load_dwordx4 v[30:33], v242, s[36:37] nt
	s_add_u32 s36, s36, 0x8000
	s_addc_u32 s37, s37, 0
	global_load_dwordx4 v[34:37], v242, s[36:37] nt
	s_add_u32 s36, s36, 0x8000
	s_addc_u32 s37, s37, 0
	global_load_dwordx4 v[38:41], v242, s[36:37] nt
	s_add_u32 s36, s36, 0x8000
	s_addc_u32 s37, s37, 0
	global_load_dwordx4 v[42:45], v242, s[36:37] nt
	s_add_u32 s36, s36, 0x8000
	s_addc_u32 s37, s37, 0
	global_load_dwordx4 v[46:49], v242, s[36:37] nt
	s_add_u32 s36, s36, 0x8000
	s_addc_u32 s37, s37, 0
	global_load_dwordx4 v[50:53], v242, s[36:37] nt
	s_add_u32 s36, s36, 0x8000
	s_addc_u32 s37, s37, 0
	global_load_dwordx4 v[54:57], v242, s[36:37] nt
	s_add_u32 s36, s36, 0x8000
	s_addc_u32 s37, s37, 0
	global_load_dwordx4 v[58:61], v242, s[36:37] nt
	s_add_u32 s36, s36, 0x8000
	s_addc_u32 s37, s37, 0
	global_load_dwordx4 v[62:65], v242, s[36:37] nt
	s_lshl_b32 s24, s23, 7
	v_lshlrev_b32_e32 v68, 7, v76
	s_lshl_b32 s23, s23, 6
	v_bfe_u32 v79, v76, 4, 2
	v_lshrrev_b32_e32 v80, 1, v76
	v_bfe_u32 v81, v76, 1, 3
	s_and_b32 s24, s24, 0x2000
	v_and_b32_e32 v68, 0x780, v68
	s_and_b32 s23, s23, 0xffffe000
	v_or_b32_e32 v146, s24, v68
	v_bitop3_b32 v69, v80, v79, 7 bitop3:0x6c
	v_or_b32_e32 v148, s23, v68
	v_bitop3_b32 v68, v79, v81, 4 bitop3:0x36
	v_lshlrev_b32_e32 v149, 4, v69
	v_lshlrev_b32_e32 v147, 4, v68
	v_mov_b64_e32 v[68:69], s[8:9]
	v_bitop3_b32 v74, v78, 7, v76 bitop3:0x48
	v_mad_i64_i32 v[68:69], s[8:9], v77, s28, v[68:69]
	v_lshlrev_b32_e32 v74, 4, v74
	v_or_b32_e32 v68, v68, v74
	s_mul_hi_i32 s8, s22, 0x880
	s_mulk_i32 s22, 0x880
	v_lshl_add_u64 v[132:133], s[90:91], 0, v[68:69]
	v_or_b32_e32 v68, s22, v74
	v_mov_b32_e32 v69, s8
	v_lshl_add_u64 v[70:71], v[68:69], 0, v[70:71]
	v_lshl_add_u64 v[66:67], v[68:69], 0, v[66:67]
	v_lshl_add_u64 v[74:75], v[68:69], 0, v[0:1]
	v_lshl_add_u64 v[136:137], s[6:7], 0, v[70:71]
	v_lshl_add_u64 v[70:71], v[68:69], 0, v[72:73]
	v_lshl_add_u64 v[140:141], s[6:7], 0, v[66:67]
	v_mov_b32_e32 v66, 0
	v_lshl_add_u64 v[134:135], s[6:7], 0, v[74:75]
	v_lshl_add_u64 v[138:139], s[6:7], 0, v[70:71]
	s_mov_b64 s[8:9], 0
	s_mov_b32 s22, 0
	v_mov_b32_e32 v67, v66
; #define MFMA16(a, b, c) __builtin_amdgcn_mfma_f32_16x16x32_bf16((a), (b), (c), 0, 0, 0)
; DI void gemm_tile(const bf16_t* __restrict__ A, int lda, const bf16_t* __restrict__ Bt, int ldb, int bvalid, int K, f32x4 (&acc)[4][4], char* lds, bool preloaded = false) {
;     ...
;   const bf16_t* ap = A + (size_t)lr * lda + ((lc ^ ((lr >> 1) & 7)) << 3);
;   const bf16_t* bp = Bt + ((lc ^ ((lr >> 1) & 7)) << 3);
;   typedef __attribute__((address_space(1))) const unsigned gptr_t;
;   typedef __attribute__((address_space(3))) unsigned lptr_t;
;   const unsigned lbase = (unsigned)(size_t)lds + (unsigned)tid * 16u;
;     ...
;   auto compute = [&](int st) {
;     const char* base = lds + st * 32768;
;     bf16x8 af[2][4], bfr[2][4];
; #pragma unroll
;     for (int s = 0; s < 2; ++s) {
;       const int ch = ((4 * s + fq) ^ fx) << 4;
; #pragma unroll
;       for (int mi = 0; mi < 4; ++mi) af[s][mi] = *(const bf16x8*)(base + (wm * 64 + mi * 16 + fr) * 128 + ch);
; #pragma unroll
;       for (int ni = 0; ni < 4; ++ni) bfr[s][ni] = *(const bf16x8*)(base + 16384 + (wn * 64 + ni * 16 + fr) * 128 + ch);
;     }
;     __builtin_amdgcn_s_setprio(1);
; #pragma unroll
;     for (int s = 0; s < 2; ++s)
; #pragma unroll
;       for (int mi = 0; mi < 4; ++mi)
; #pragma unroll
;         for (int ni = 0; ni < 4; ++ni) acc[mi][ni] = MFMA16(af[s][mi], bfr[s][ni], acc[mi][ni]);
;     __builtin_amdgcn_s_setprio(0);
;   };
;   const int nk = K >> 6;
;   if (!preloaded) { GLDS(0, 0) }
;   __syncthreads();
;   for (int kt = 0; kt < nk; ++kt) {
;     if (kt + 1 < nk) { GLDS((kt + 1) & 1, (kt + 1) << 6) }
;     compute(kt & 1);
;     __syncthreads();
	v_mov_b32_e32 v68, v66
	v_mov_b32_e32 v69, v66
	v_mov_b32_e32 v70, v66
	v_mov_b32_e32 v71, v66
	v_mov_b32_e32 v72, v66
	v_mov_b32_e32 v73, v66
	v_mov_b32_e32 v74, v66
	v_mov_b32_e32 v75, v66
	v_mov_b32_e32 v76, v66
	v_mov_b32_e32 v77, v66
	v_mov_b32_e32 v78, v66
	v_mov_b32_e32 v79, v66
	v_mov_b32_e32 v80, v66
	v_mov_b32_e32 v81, v66
	v_mov_b32_e32 v82, v66
	v_mov_b32_e32 v83, v66
	v_mov_b32_e32 v84, v66
	v_mov_b32_e32 v85, v66
	v_mov_b32_e32 v86, v66
	v_mov_b32_e32 v87, v66
	v_mov_b32_e32 v88, v66
	v_mov_b32_e32 v89, v66
	v_mov_b32_e32 v90, v66
	v_mov_b32_e32 v91, v66
	v_mov_b32_e32 v92, v66
	v_mov_b32_e32 v93, v66
	v_mov_b32_e32 v94, v66
	v_mov_b32_e32 v95, v66
	v_mov_b32_e32 v96, v66
	v_mov_b32_e32 v97, v66
	v_mov_b32_e32 v98, v66
	v_mov_b32_e32 v99, v66
	v_mov_b32_e32 v100, v66
	v_mov_b32_e32 v101, v66
	v_mov_b32_e32 v102, v66
	v_mov_b32_e32 v103, v66
	v_mov_b32_e32 v104, v66
	v_mov_b32_e32 v105, v66
	v_mov_b32_e32 v106, v66
	v_mov_b32_e32 v107, v66
	v_mov_b32_e32 v108, v66
	v_mov_b32_e32 v109, v66
	v_mov_b32_e32 v110, v66
	v_mov_b32_e32 v111, v66
	v_mov_b32_e32 v112, v66
	v_mov_b32_e32 v113, v66
	v_mov_b32_e32 v114, v66
	v_mov_b32_e32 v115, v66
	v_mov_b32_e32 v116, v66
	v_mov_b32_e32 v117, v66
	v_mov_b32_e32 v118, v66
	v_mov_b32_e32 v119, v66
	v_mov_b32_e32 v120, v66
	v_mov_b32_e32 v121, v66
	v_mov_b32_e32 v122, v66
	v_mov_b32_e32 v123, v66
	v_mov_b32_e32 v124, v66
	v_mov_b32_e32 v125, v66
	v_mov_b32_e32 v126, v66
	v_mov_b32_e32 v127, v66
	v_mov_b32_e32 v128, v66
	v_mov_b32_e32 v129, v66
	v_lshrrev_b32_e32 v246, 3, v158
	v_bfe_u32 v247, v158, 4, 3
	v_and_b32_e32 v0, 7, v158
	v_xor_b32_e32 v0, v0, v247
	v_lshlrev_b32_e32 v0, 4, v0
	v_mul_u32_u24_e32 v246, 0x880, v246
	v_add_u32_e32 v242, v246, v0
	v_add_u32_e32 v243, 0x11000, v242
	v_add_u32_e32 v244, 0x22000, v242
	v_add_u32_e32 v245, 0x33000, v242
	v_readfirstlane_b32 s50, v145
	s_and_b32 s24, s22, 0x8000
	v_or_b32_e32 v0, s24, v149
	v_add_u32_e32 v246, v0, v148
	v_add_u32_e32 v247, v0, v146
	s_waitcnt vmcnt(16) lgkmcnt(0)
	s_barrier
	.p2alignl 6, 3212836864
.LBB0_170:
	s_add_i32 s23, s22, 0x8000
	s_and_b32 s24, s23, 0x8000
	s_and_b32 s22, s22, 0x8000
	ds_read_b128 v[150:153], v246
	ds_read_b128 v[188:191], v247 offset:16384
	ds_read_b128 v[192:195], v247 offset:18432
	ds_read_b128 v[196:199], v247 offset:20480
	ds_read_b128 v[200:203], v247 offset:22528
	ds_read_b128 v[154:157], v246 offset:2048
	ds_read_b128 v[180:183], v246 offset:4096
	ds_read_b128 v[184:187], v246 offset:6144
	s_add_i32 m0, s50, s24
	v_or_b32_e32 v0, s22, v147
	global_load_lds_dwordx4 v242, s[40:41]
	s_addk_i32 m0, 0x1000
	v_add_u32_e32 v179, v0, v148
	global_load_lds_dwordx4 v243, s[40:41]
	s_addk_i32 m0, 0x1000
	v_add_u32_e32 v0, v0, v146
	global_load_lds_dwordx4 v244, s[40:41]
	s_addk_i32 m0, 0x1000
	ds_read_b128 v[204:207], v179
	global_load_lds_dwordx4 v245, s[40:41]
	s_addk_i32 m0, 0x1000
	ds_read_b128 v[220:223], v0 offset:16384
	global_load_lds_dwordx4 v242, s[42:43]
	s_addk_i32 m0, 0x1000
	ds_read_b128 v[224:227], v0 offset:18432
	global_load_lds_dwordx4 v243, s[42:43]
	s_addk_i32 m0, 0x1000
	ds_read_b128 v[228:231], v0 offset:20480
	global_load_lds_dwordx4 v244, s[42:43]
	s_addk_i32 m0, 0x1000
	ds_read_b128 v[232:235], v0 offset:22528
	global_load_lds_dwordx4 v245, s[42:43]
	ds_read_b128 v[208:211], v179 offset:2048
	ds_read_b128 v[212:215], v179 offset:4096
	ds_read_b128 v[216:219], v179 offset:6144
	s_add_u32 s40, s40, 0x80
	s_addc_u32 s41, s41, 0
	s_add_u32 s42, s42, 0x80
	s_addc_u32 s43, s43, 0
	s_setprio 1
	s_waitcnt lgkmcnt(11)
	v_mfma_f32_16x16x32_bf16 v[126:129], v[150:153], v[188:191], v[126:129]
	v_mfma_f32_16x16x32_bf16 v[122:125], v[150:153], v[192:195], v[122:125]
	v_mfma_f32_16x16x32_bf16 v[118:121], v[150:153], v[196:199], v[118:121]
	v_mfma_f32_16x16x32_bf16 v[114:117], v[150:153], v[200:203], v[114:117]
	s_waitcnt lgkmcnt(8)
	v_mfma_f32_16x16x32_bf16 v[110:113], v[154:157], v[188:191], v[110:113]
	v_mfma_f32_16x16x32_bf16 v[106:109], v[154:157], v[192:195], v[106:109]
	v_mfma_f32_16x16x32_bf16 v[102:105], v[154:157], v[196:199], v[102:105]
	v_mfma_f32_16x16x32_bf16 v[98:101], v[154:157], v[200:203], v[98:101]
	v_mfma_f32_16x16x32_bf16 v[94:97], v[180:183], v[188:191], v[94:97]
	v_mfma_f32_16x16x32_bf16 v[90:93], v[180:183], v[192:195], v[90:93]
	v_mfma_f32_16x16x32_bf16 v[86:89], v[180:183], v[196:199], v[86:89]
	v_mfma_f32_16x16x32_bf16 v[82:85], v[180:183], v[200:203], v[82:85]
	v_mfma_f32_16x16x32_bf16 v[78:81], v[184:187], v[188:191], v[78:81]
	v_mfma_f32_16x16x32_bf16 v[74:77], v[184:187], v[192:195], v[74:77]
	v_mfma_f32_16x16x32_bf16 v[70:73], v[184:187], v[196:199], v[70:73]
	v_mfma_f32_16x16x32_bf16 v[66:69], v[184:187], v[200:203], v[66:69]
	s_waitcnt lgkmcnt(3)
	v_mfma_f32_16x16x32_bf16 v[126:129], v[204:207], v[220:223], v[126:129]
	v_mfma_f32_16x16x32_bf16 v[122:125], v[204:207], v[224:227], v[122:125]
	v_mfma_f32_16x16x32_bf16 v[118:121], v[204:207], v[228:231], v[118:121]
	v_mfma_f32_16x16x32_bf16 v[114:117], v[204:207], v[232:235], v[114:117]
	s_waitcnt lgkmcnt(0)
	v_mfma_f32_16x16x32_bf16 v[110:113], v[208:211], v[220:223], v[110:113]
	v_mfma_f32_16x16x32_bf16 v[106:109], v[208:211], v[224:227], v[106:109]
	v_mfma_f32_16x16x32_bf16 v[102:105], v[208:211], v[228:231], v[102:105]
	v_mfma_f32_16x16x32_bf16 v[98:101], v[208:211], v[232:235], v[98:101]
	v_mfma_f32_16x16x32_bf16 v[94:97], v[212:215], v[220:223], v[94:97]
	v_mfma_f32_16x16x32_bf16 v[90:93], v[212:215], v[224:227], v[90:93]
	v_mfma_f32_16x16x32_bf16 v[86:89], v[212:215], v[228:231], v[86:89]
	v_mfma_f32_16x16x32_bf16 v[82:85], v[212:215], v[232:235], v[82:85]
	v_mfma_f32_16x16x32_bf16 v[78:81], v[216:219], v[220:223], v[78:81]
	v_mfma_f32_16x16x32_bf16 v[74:77], v[216:219], v[224:227], v[74:77]
	v_mfma_f32_16x16x32_bf16 v[70:73], v[216:219], v[228:231], v[70:73]
	v_mfma_f32_16x16x32_bf16 v[66:69], v[216:219], v[232:235], v[66:69]
	s_setprio 0
	v_or_b32_e32 v0, s24, v149
	v_add_u32_e32 v246, v0, v148
	v_add_u32_e32 v247, v0, v146
	s_add_u32 s8, s8, 0x80
	s_addc_u32 s9, s9, 0
	s_cmpk_eq_i32 s8, 0x780
	s_mov_b32 s22, s23
	s_waitcnt vmcnt(0)
	s_barrier
; #define MFMA16(a, b, c) __builtin_amdgcn_mfma_f32_16x16x32_bf16((a), (b), (c), 0, 0, 0)
; DI void gemm_tile(const bf16_t* __restrict__ A, int lda, const bf16_t* __restrict__ Bt, int ldb, int bvalid, int K, f32x4 (&acc)[4][4], char* lds, bool preloaded = false) {
;     ...
;   auto compute = [&](int st) {
;     const char* base = lds + st * 32768;
;     bf16x8 af[2][4], bfr[2][4];
; #pragma unroll
;     for (int s = 0; s < 2; ++s) {
;       const int ch = ((4 * s + fq) ^ fx) << 4;
; #pragma unroll
;       for (int mi = 0; mi < 4; ++mi) af[s][mi] = *(const bf16x8*)(base + (wm * 64 + mi * 16 + fr) * 128 + ch);
; #pragma unroll
;       for (int ni = 0; ni < 4; ++ni) bfr[s][ni] = *(const bf16x8*)(base + 16384 + (wn * 64 + ni * 16 + fr) * 128 + ch);
;     }
;     __builtin_amdgcn_s_setprio(1);
; #pragma unroll
;     for (int s = 0; s < 2; ++s)
; #pragma unroll
;       for (int mi = 0; mi < 4; ++mi)
; #pragma unroll
;         for (int ni = 0; ni < 4; ++ni) acc[mi][ni] = MFMA16(af[s][mi], bfr[s][ni], acc[mi][ni]);
;     __builtin_amdgcn_s_setprio(0);
; DI void phaseE_tile(const P& p, int layer, int mt, int nt, char* lds) {
;     ...
;   float* tile = (float*)lds;
;   stage_acc(acc, tile, wm, wn, fr, fq);
;   __syncthreads();
;   bf16_t* XB = (bf16_t*)(p.ws + W_XB);
;   float* SS = (float*)(p.ws + W_SS);
; #pragma unroll
;   for (int ps = 0; ps < 16; ++ps) {
;     const int lr = ps * 8 + wm * 4 + fq, row = row0 + lr;
;     const f32x4 v = xr[ps] + *(const f32x4*)(tile + lr * EPS + wn * 64 + fr * 4);
;     *(f32x4*)(XF + (size_t)row * DM + col) = v;
	s_cbranch_scc0 .LBB0_170
	v_add_u32_e32 v0, v149, v148
	ds_read_b128 v[132:135], v0 offset:32768
	ds_read_b128 v[136:139], v0 offset:34816
	ds_read_b128 v[150:153], v0 offset:36864
	ds_read_b128 v[154:157], v0 offset:38912
	v_add_u32_e32 v0, v149, v146
	ds_read_b128 v[180:183], v0 offset:49152
	ds_read_b128 v[184:187], v0 offset:51200
	ds_read_b128 v[188:191], v0 offset:53248
	ds_read_b128 v[192:195], v0 offset:55296
	v_add_u32_e32 v0, v147, v148
	ds_read_b128 v[196:199], v0 offset:32768
	ds_read_b128 v[200:203], v0 offset:34816
	ds_read_b128 v[204:207], v0 offset:36864
	ds_read_b128 v[208:211], v0 offset:38912
	v_add_u32_e32 v0, v147, v146
	ds_read_b128 v[146:149], v0 offset:49152
	ds_read_b128 v[212:215], v0 offset:51200
	ds_read_b128 v[216:219], v0 offset:53248
	ds_read_b128 v[220:223], v0 offset:55296
	s_setprio 1
	s_waitcnt lgkmcnt(9)
	v_mfma_f32_16x16x32_bf16 v[70:73], v[154:157], v[188:191], v[70:73]
	s_waitcnt lgkmcnt(8)
	v_mfma_f32_16x16x32_bf16 v[66:69], v[154:157], v[192:195], v[66:69]
	v_mfma_f32_16x16x32_bf16 v[126:129], v[132:135], v[180:183], v[126:129]
	v_mfma_f32_16x16x32_bf16 v[122:125], v[132:135], v[184:187], v[122:125]
	v_mfma_f32_16x16x32_bf16 v[118:121], v[132:135], v[188:191], v[118:121]
	v_mfma_f32_16x16x32_bf16 v[114:117], v[132:135], v[192:195], v[114:117]
	v_mfma_f32_16x16x32_bf16 v[110:113], v[136:139], v[180:183], v[110:113]
	v_mfma_f32_16x16x32_bf16 v[106:109], v[136:139], v[184:187], v[106:109]
	v_mfma_f32_16x16x32_bf16 v[102:105], v[136:139], v[188:191], v[102:105]
	v_mfma_f32_16x16x32_bf16 v[98:101], v[136:139], v[192:195], v[98:101]
	v_mfma_f32_16x16x32_bf16 v[94:97], v[150:153], v[180:183], v[94:97]
	v_mfma_f32_16x16x32_bf16 v[90:93], v[150:153], v[184:187], v[90:93]
	v_mfma_f32_16x16x32_bf16 v[86:89], v[150:153], v[188:191], v[86:89]
	v_mfma_f32_16x16x32_bf16 v[82:85], v[150:153], v[192:195], v[82:85]
	v_mfma_f32_16x16x32_bf16 v[78:81], v[154:157], v[180:183], v[78:81]
	v_mfma_f32_16x16x32_bf16 v[74:77], v[154:157], v[184:187], v[74:77]
	s_waitcnt lgkmcnt(1)
	v_mfma_f32_16x16x32_bf16 v[70:73], v[208:211], v[216:219], v[70:73]
	s_waitcnt lgkmcnt(0)
	v_mfma_f32_16x16x32_bf16 v[66:69], v[208:211], v[220:223], v[66:69]
	v_mfma_f32_16x16x32_bf16 v[126:129], v[196:199], v[146:149], v[126:129]
	v_mfma_f32_16x16x32_bf16 v[122:125], v[196:199], v[212:215], v[122:125]
	v_mfma_f32_16x16x32_bf16 v[118:121], v[196:199], v[216:219], v[118:121]
	v_mfma_f32_16x16x32_bf16 v[114:117], v[196:199], v[220:223], v[114:117]
	v_mfma_f32_16x16x32_bf16 v[110:113], v[200:203], v[146:149], v[110:113]
	v_mfma_f32_16x16x32_bf16 v[106:109], v[200:203], v[212:215], v[106:109]
	v_mfma_f32_16x16x32_bf16 v[102:105], v[200:203], v[216:219], v[102:105]
	v_mfma_f32_16x16x32_bf16 v[98:101], v[200:203], v[220:223], v[98:101]
	v_mfma_f32_16x16x32_bf16 v[94:97], v[204:207], v[146:149], v[94:97]
	v_mfma_f32_16x16x32_bf16 v[90:93], v[204:207], v[212:215], v[90:93]
	v_mfma_f32_16x16x32_bf16 v[86:89], v[204:207], v[216:219], v[86:89]
	v_mfma_f32_16x16x32_bf16 v[82:85], v[204:207], v[220:223], v[82:85]
	v_mfma_f32_16x16x32_bf16 v[78:81], v[208:211], v[146:149], v[78:81]
	v_mfma_f32_16x16x32_bf16 v[74:77], v[208:211], v[212:215], v[74:77]
	s_setprio 0
	v_lshlrev_b32_e32 v0, 2, v142
	v_lshl_or_b32 v132, s20, 6, v0
	v_lshl_or_b32 v0, s19, 8, v144
	v_mad_u64_u32 v[132:133], s[8:9], v132, s56, v[0:1]
	v_add_u32_e32 v0, 0x400, v132
	s_barrier
	ds_write2_b32 v132, v126, v122 offset1:16
	ds_write2_b32 v132, v127, v123 offset0:132 offset1:148
	ds_write2_b32 v0, v128, v124 offset0:8 offset1:24
	ds_write2_b32 v0, v129, v125 offset0:140 offset1:156
	ds_write2_b32 v132, v118, v114 offset0:32 offset1:48
	ds_write2_b32 v132, v119, v115 offset0:164 offset1:180
	ds_write2_b32 v0, v120, v116 offset0:40 offset1:56
	ds_write2_b32 v0, v121, v117 offset0:172 offset1:188
	v_add_u32_e32 v0, 0x2000, v132
	ds_write2_b32 v0, v110, v106 offset0:64 offset1:80
	ds_write2_b32 v0, v111, v107 offset0:196 offset1:212
	v_add_u32_e32 v106, 0x2400, v132
	ds_write2_b32 v106, v112, v108 offset0:72 offset1:88
	ds_write2_b32 v106, v113, v109 offset0:204 offset1:220
	ds_write2_b32 v0, v102, v98 offset0:96 offset1:112
	ds_write2_b32 v0, v103, v99 offset0:228 offset1:244
	ds_write2_b32 v106, v104, v100 offset0:104 offset1:120
	ds_write2_b32 v106, v105, v101 offset0:236 offset1:252
	v_add_u32_e32 v0, 0x4000, v132
	ds_write2_b32 v0, v94, v90 offset0:128 offset1:144
	v_add_u32_e32 v90, 0x4400, v132
	ds_write2_b32 v90, v95, v91 offset0:4 offset1:20
	ds_write2_b32 v90, v96, v92 offset0:136 offset1:152
	v_add_u32_e32 v91, 0x4800, v132
	ds_write2_b32 v91, v97, v93 offset0:12 offset1:28
	ds_write2_b32 v0, v86, v82 offset0:160 offset1:176
	ds_write2_b32 v90, v87, v83 offset0:36 offset1:52
	ds_write2_b32 v90, v88, v84 offset0:168 offset1:184
	ds_write2_b32 v91, v89, v85 offset0:44 offset1:60
	v_add_u32_e32 v0, 0x6000, v132
	ds_write2_b32 v0, v78, v74 offset0:192 offset1:208
	v_add_u32_e32 v74, 0x6400, v132
	ds_write2_b32 v74, v79, v75 offset0:68 offset1:84
	ds_write2_b32 v74, v80, v76 offset0:200 offset1:216
	v_add_u32_e32 v75, 0x6800, v132
	ds_write2_b32 v75, v81, v77 offset0:76 offset1:92
	ds_write2_b32 v0, v70, v66 offset0:224 offset1:240
	ds_write2_b32 v74, v71, v67 offset0:100 offset1:116
	ds_write2_b32 v74, v72, v68 offset0:232 offset1:248
	ds_write2_b32 v75, v73, v69 offset0:108 offset1:124
	v_or_b32_e32 v68, s11, v142
	v_lshlrev_b32_e32 v0, 2, v144
	v_lshl_add_u32 v0, s21, 2, v0
	v_mul_lo_u32 v66, v68, s56
	v_add_u32_e32 v0, v0, v66
	s_waitcnt lgkmcnt(0)
	s_barrier
	ds_read_b128 v[180:183], v0
	ds_read_b128 v[184:187], v0 offset:4224
	ds_read_b128 v[188:191], v0 offset:8448
	ds_read_b128 v[192:195], v0 offset:12672
	ds_read_b128 v[196:199], v0 offset:16896
	ds_read_b128 v[200:203], v0 offset:21120
	ds_read_b128 v[204:207], v0 offset:25344
	ds_read_b128 v[208:211], v0 offset:29568
	ds_read_b128 v[212:215], v0 offset:33792
	ds_read_b128 v[216:219], v0 offset:38016
	ds_read_b128 v[220:223], v0 offset:42240
	ds_read_b128 v[224:227], v0 offset:46464
	ds_read_b128 v[228:231], v0 offset:50688
	ds_read_b128 v[232:235], v0 offset:54912
	ds_read_b128 v[150:153], v0 offset:59136
	ds_read_b128 v[154:157], v0 offset:63360
	v_add_u32_e32 v70, s10, v68
	v_ashrrev_i32_e32 v71, 31, v70
	v_lshl_add_u64 v[66:67], v[130:131], 2, s[88:89]
	v_lshlrev_b64 v[68:69], 12, v[70:71]
	s_waitcnt lgkmcnt(15)
	v_pk_add_f32 v[4:5], v[4:5], v[182:183]
	v_pk_add_f32 v[2:3], v[2:3], v[180:181]
	v_lshl_add_u64 v[68:69], v[66:67], 0, v[68:69]
	s_and_b64 vcc, exec, s[38:39]
	s_mov_b64 s[8:9], -1
	global_store_dwordx4 v[68:69], v[2:5], off
	s_cbranch_vccnz .LBB0_173
	s_mov_b64 s[8:9], 0
